# HGRN recurrence: loader waves (the pole) run at s_setprio 3 above the recurrence waves
# speedup vs baseline: 1.0138x; 1.0078x over previous
; __device__ __forceinline__ void hgrn_unit(LAS unsigned char* lds, int b, int h, const bf16* Q, const bf16* KK, const bf16* V, const bf16* PBUF, const float* DBUF, bf16* Y, const float* onw) {
;     ...
;     if (!cw) {
;         const int lt = tid - 256;
;         v4u lqA[4], lkA[4], lvA[4], lpA[2], ldA;
;     ...
;         const int foct = lt & 15;
;         const f32x4 fw0 = *(const f32x4*)(onw + 8 * foct), fw1 = *(const f32x4*)(onw + 8 * foct + 4);
.LBB0_1283:
	v_mov_b32_e32 v1, v145
	s_nop 0
	v_readfirstlane_b32 s0, v1
	s_ashr_i32 s14, s0, 6
	s_cmp_lt_i32 s14, 4
	s_mov_b64 s[0:1], -1
	s_cbranch_scc1 .LBB0_1305
	s_setprio 3
	s_ashr_i32 s6, s13, 3
	s_waitcnt vmcnt(2)
	v_add_u32_e32 v97, 0xffffff00, v1
	v_add_u32_e32 v34, 0x100, v1
	v_add_u32_e32 v44, 0x200, v1
	s_and_b32 s0, s13, 7
	v_lshlrev_b32_e32 v71, 3, v1
	s_ashr_i32 s7, s6, 31
	v_ashrrev_i32_e32 v92, 4, v97
	v_ashrrev_i32_e32 v90, 4, v1
	v_ashrrev_i32_e32 v88, 4, v34
	v_ashrrev_i32_e32 v86, 4, v44
	s_waitcnt vmcnt(1)
	v_and_b32_e32 v96, 0x78, v71
	s_lshl_b64 s[2:3], s[6:7], 11
	s_lshl_b32 s18, s0, 7
	v_ashrrev_i32_e32 v93, 31, v92
	v_ashrrev_i32_e32 v91, 31, v90
	v_ashrrev_i32_e32 v89, 31, v88
	v_ashrrev_i32_e32 v87, 31, v86
	s_lshl_b32 s15, s6, 8
	s_lshl_b32 s1, s0, 5
	v_or_b32_e32 v12, s18, v96
	v_lshl_add_u64 v[10:11], s[2:3], 0, v[92:93]
	v_lshl_add_u64 v[20:21], s[2:3], 0, v[90:91]
	v_lshl_add_u64 v[34:35], s[2:3], 0, v[88:89]
	v_lshl_add_u64 v[44:45], s[2:3], 0, v[86:87]
	s_or_b32 s8, s1, s15
	s_waitcnt vmcnt(0)
	v_lshlrev_b64 v[82:83], 11, v[10:11]
	v_lshlrev_b32_e32 v70, 1, v12
	v_readlane_b32 s0, v253, 0
	v_lshlrev_b64 v[84:85], 11, v[20:21]
	v_lshlrev_b64 v[110:111], 11, v[34:35]
	v_lshlrev_b64 v[112:113], 11, v[44:45]
	v_or_b32_e32 v18, v82, v70
	v_mov_b32_e32 v19, v83
	v_readlane_b32 s1, v253, 1
	v_or_b32_e32 v26, v84, v70
	v_mov_b32_e32 v27, v85
	v_or_b32_e32 v42, v110, v70
	v_mov_b32_e32 v43, v111
	v_or_b32_e32 v50, v112, v70
	v_mov_b32_e32 v51, v113
	s_ashr_i32 s9, s8, 31
	v_lshl_add_u64 v[14:15], s[0:1], 0, v[18:19]
	v_lshl_add_u64 v[28:29], s[0:1], 0, v[26:27]
	v_lshl_add_u64 v[38:39], s[0:1], 0, v[42:43]
	v_lshl_add_u64 v[52:53], s[0:1], 0, v[50:51]
	s_lshl_b64 s[0:1], s[8:9], 13
	v_lshlrev_b32_e32 v98, 3, v97
	v_readlane_b32 s10, v253, 13
	s_add_u32 s0, s80, s0
	v_add_u32_e32 v100, 0x800, v98
	v_readlane_b32 s11, v253, 14
	s_addc_u32 s1, s81, s1
	v_ashrrev_i32_e32 v99, 31, v98
	v_ashrrev_i32_e32 v101, 31, v100
	v_lshlrev_b32_e32 v6, 2, v96
	v_lshl_add_u64 v[10:11], s[34:35], 0, v[18:19]
	v_lshl_add_u64 v[18:19], s[10:11], 0, v[18:19]
	v_lshl_add_u64 v[20:21], s[34:35], 0, v[26:27]
	v_lshl_add_u64 v[30:31], s[10:11], 0, v[26:27]
	v_lshl_add_u64 v[34:35], s[34:35], 0, v[42:43]
	v_lshl_add_u64 v[42:43], s[10:11], 0, v[42:43]
	v_lshl_add_u64 v[44:45], s[34:35], 0, v[50:51]
	v_lshl_add_u64 v[54:55], s[10:11], 0, v[50:51]
	v_lshl_add_u64 v[58:59], v[98:99], 1, s[0:1]
	v_lshl_add_u64 v[60:61], v[100:101], 1, s[0:1]
	global_load_dwordx4 v[2:5], v6, s[4:5] offset:16
	s_nop 0
	global_load_dwordx4 v[6:9], v6, s[4:5]
	s_nop 0
	global_load_dwordx4 v[10:13], v[10:11], off
	s_nop 0
	global_load_dwordx4 v[14:17], v[14:15], off
	s_nop 0
	global_load_dwordx4 v[22:25], v[18:19], off
	s_nop 0
	global_load_dwordx4 v[18:21], v[20:21], off
	s_nop 0
	global_load_dwordx4 v[26:29], v[28:29], off
	s_nop 0
	global_load_dwordx4 v[30:33], v[30:31], off
	s_nop 0
	global_load_dwordx4 v[34:37], v[34:35], off
	s_nop 0
	global_load_dwordx4 v[38:41], v[38:39], off
	s_nop 0
	global_load_dwordx4 v[46:49], v[42:43], off
	s_nop 0
	global_load_dwordx4 v[42:45], v[44:45], off
	s_nop 0
	global_load_dwordx4 v[50:53], v[52:53], off
	s_nop 0
	global_load_dwordx4 v[54:57], v[54:55], off
	s_nop 0
	global_load_dwordx4 v[62:65], v[58:59], off
	s_nop 0
	global_load_dwordx4 v[58:61], v[60:61], off
	s_movk_i32 s0, 0x11f
	v_cmp_lt_i32_e32 vcc, s0, v1
	s_movk_i32 s0, 0x120
	v_lshlrev_b32_e32 v114, 2, v97
	v_cmp_gt_i32_e64 s[0:1], s0, v1
	v_mov_b32_e32 v66, 0
	v_ashrrev_i32_e32 v115, 31, v114
	v_mov_b32_e32 v67, 0
	v_mov_b32_e32 v68, 0
	v_mov_b32_e32 v69, 0
	s_and_saveexec_b64 s[10:11], s[0:1]
	s_cbranch_execz .LBB0_1286
	s_lshl_b64 s[20:21], s[8:9], 9
	v_readlane_b32 s22, v252, 39
	v_readlane_b32 s23, v252, 40
	s_add_u32 s20, s22, s20
	s_addc_u32 s21, s23, s21
	v_lshl_add_u64 v[66:67], v[114:115], 2, s[20:21]
	global_load_dwordx4 v[66:69], v[66:67], off

.LBB0_1304:
	s_waitcnt vmcnt(8)
	v_readlane_b32 s1, v255, 0
	v_readlane_b32 s0, v254, 63
	s_or_b32 s2, s2, 0x7c0
	s_waitcnt vmcnt(12)
	v_add_u32_e32 v22, s1, v136
	ds_read_b128 v[18:21], v22
	ds_read_b128 v[22:25], v22 offset:16
	s_waitcnt vmcnt(5)
	v_lshl_add_u32 v50, v96, 1, s0
	s_mov_b32 s0, 0x358637bd
	s_waitcnt vmcnt(3)
	v_lshlrev_b32_e32 v34, 16, v82
	s_waitcnt lgkmcnt(1)
	v_mov_b32_e32 v26, v18
	s_waitcnt lgkmcnt(0)
	v_mov_b32_e32 v27, v22
	v_mov_b32_e32 v22, v19
	v_add_u32_e32 v18, v50, v134
	v_pk_add_f32 v[22:23], v[26:27], v[22:23]
	v_mov_b32_e32 v26, v20
	v_mov_b32_e32 v27, v24
	v_mov_b32_e32 v24, v21
	ds_read_b128 v[18:21], v18
	v_pk_add_f32 v[24:25], v[26:27], v[24:25]
	v_add_u32_e32 v26, s1, v133
	v_pk_add_f32 v[30:31], v[22:23], v[24:25]
	ds_read_b128 v[22:25], v26
	s_waitcnt lgkmcnt(1)
	v_lshlrev_b32_e32 v32, 16, v18
	v_and_b32_e32 v33, 0xffff0000, v18
	v_lshlrev_b32_e32 v36, 16, v19
	v_and_b32_e32 v37, 0xffff0000, v19
	v_lshlrev_b32_e32 v40, 16, v20
	v_and_b32_e32 v41, 0xffff0000, v20
	v_lshlrev_b32_e32 v44, 16, v21
	v_and_b32_e32 v45, 0xffff0000, v21
	ds_read_b128 v[18:21], v26 offset:16
	s_waitcnt lgkmcnt(1)
	v_mov_b32_e32 v48, v22
	v_add_u32_e32 v22, v50, v132
	ds_read_b128 v[26:29], v22
	v_mov_b32_e32 v22, v24
	s_waitcnt lgkmcnt(1)
	v_mov_b32_e32 v49, v18
	v_mov_b32_e32 v18, v23
	v_mov_b32_e32 v23, v20
	v_mov_b32_e32 v20, v25
	v_pk_add_f32 v[18:19], v[48:49], v[18:19]
	v_pk_add_f32 v[20:21], v[22:23], v[20:21]
	v_and_b32_e32 v35, 0xffff0000, v82
	v_pk_add_f32 v[18:19], v[18:19], v[20:21]
	v_mov_b32_e32 v21, v30
	v_mov_b32_e32 v20, v18
	v_mov_b32_e32 v30, v19
	v_pk_add_f32 v[18:19], v[20:21], v[30:31]
	v_mov_b64_e32 v[30:31], s[0:1]
	s_brev_b32 s0, 60
	v_pk_fma_f32 v[22:23], v[18:19], s[0:1], v[30:31] op_sel_hi:[1,0,0]
	v_lshlrev_b32_e32 v38, 16, v83
	v_mul_f32_e32 v18, 0x4b800000, v23
	v_cmp_gt_f32_e32 vcc, s33, v23
	v_and_b32_e32 v39, 0xffff0000, v83
	v_lshlrev_b32_e32 v42, 16, v84
	v_cndmask_b32_e32 v18, v23, v18, vcc
	v_rsq_f32_e32 v20, v18
	v_lshl_add_u64 v[18:19], s[2:3], 0, v[92:93]
	v_lshlrev_b64 v[18:19], 11, v[18:19]
	v_lshl_add_u64 v[24:25], v[94:95], 0, v[18:19]
	v_mul_f32_e32 v18, 0x45800000, v20
	v_cndmask_b32_e32 v48, v20, v18, vcc
	v_pk_mul_f32 v[18:19], v[48:49], v[32:33] op_sel_hi:[0,1]
	v_pk_mul_f32 v[20:21], v[48:49], v[36:37] op_sel_hi:[0,1]
	v_pk_mul_f32 v[18:19], v[6:7], v[18:19]
	v_pk_mul_f32 v[20:21], v[8:9], v[20:21]
	v_pk_mul_f32 v[18:19], v[18:19], v[34:35]
	v_pk_mul_f32 v[20:21], v[20:21], v[38:39]
	v_cvt_pk_bf16_f32 v18, v18, v19
	v_cvt_pk_bf16_f32 v19, v20, v21
	v_pk_mul_f32 v[20:21], v[48:49], v[40:41] op_sel_hi:[0,1]
	v_and_b32_e32 v43, 0xffff0000, v84
	v_pk_mul_f32 v[20:21], v[2:3], v[20:21]
	v_cmp_gt_f32_e32 vcc, s33, v22
	v_pk_mul_f32 v[20:21], v[20:21], v[42:43]
	v_pk_mul_f32 v[32:33], v[48:49], v[44:45] op_sel_hi:[0,1]
	v_cvt_pk_bf16_f32 v20, v20, v21
	v_mul_f32_e32 v21, 0x4b800000, v22
	v_cndmask_b32_e32 v21, v22, v21, vcc
	v_rsq_f32_e32 v34, v21
	v_lshlrev_b32_e32 v46, 16, v85
	v_and_b32_e32 v47, 0xffff0000, v85
	v_pk_mul_f32 v[32:33], v[4:5], v[32:33]
	v_add_u32_e32 v45, s1, v103
	v_pk_mul_f32 v[22:23], v[32:33], v[46:47]
	v_lshl_add_u64 v[32:33], s[2:3], 0, v[90:91]
	v_cvt_pk_bf16_f32 v21, v22, v23
	global_store_dwordx4 v[24:25], v[18:21], off
	s_waitcnt vmcnt(3)
	v_lshlrev_b32_e32 v24, 16, v67
	v_and_b32_e32 v25, 0xffff0000, v67
	v_mul_f32_e32 v18, 0x45800000, v34
	v_cndmask_b32_e32 v22, v34, v18, vcc
	s_waitcnt lgkmcnt(0)
	v_lshlrev_b32_e32 v18, 16, v26
	v_and_b32_e32 v19, 0xffff0000, v26
	v_pk_mul_f32 v[18:19], v[22:23], v[18:19] op_sel_hi:[0,1]
	v_pk_mul_f32 v[18:19], v[6:7], v[18:19]
	v_lshlrev_b32_e32 v20, 16, v66
	v_and_b32_e32 v21, 0xffff0000, v66
	v_pk_mul_f32 v[18:19], v[18:19], v[20:21]
	v_lshlrev_b32_e32 v20, 16, v27
	v_and_b32_e32 v21, 0xffff0000, v27
	v_pk_mul_f32 v[20:21], v[22:23], v[20:21] op_sel_hi:[0,1]
	v_pk_mul_f32 v[20:21], v[8:9], v[20:21]
	v_cvt_pk_bf16_f32 v18, v18, v19
	v_pk_mul_f32 v[20:21], v[20:21], v[24:25]
	v_lshlrev_b32_e32 v24, 16, v68
	v_cvt_pk_bf16_f32 v19, v20, v21
	v_lshlrev_b32_e32 v20, 16, v28
	v_and_b32_e32 v21, 0xffff0000, v28
	v_pk_mul_f32 v[20:21], v[22:23], v[20:21] op_sel_hi:[0,1]
	v_pk_mul_f32 v[20:21], v[2:3], v[20:21]
	v_and_b32_e32 v25, 0xffff0000, v68
	v_pk_mul_f32 v[20:21], v[20:21], v[24:25]
	v_lshlrev_b32_e32 v24, 16, v29
	v_and_b32_e32 v25, 0xffff0000, v29
	v_pk_mul_f32 v[22:23], v[22:23], v[24:25] op_sel_hi:[0,1]
	v_pk_mul_f32 v[22:23], v[4:5], v[22:23]
	v_lshlrev_b32_e32 v24, 16, v69
	v_and_b32_e32 v25, 0xffff0000, v69
	v_pk_mul_f32 v[22:23], v[22:23], v[24:25]
	v_add_u32_e32 v26, s1, v107
	v_cvt_pk_bf16_f32 v20, v20, v21
	v_cvt_pk_bf16_f32 v21, v22, v23
	ds_read_b128 v[22:25], v26
	ds_read_b128 v[26:29], v26 offset:16
	v_lshlrev_b64 v[32:33], 11, v[32:33]
	v_lshl_add_u64 v[32:33], v[94:95], 0, v[32:33]
	global_store_dwordx4 v[32:33], v[18:21], off
	s_waitcnt vmcnt(3)
; __device__ __forceinline__ void hgrn_unit(LAS unsigned char* lds, int b, int h, const bf16* Q, const bf16* KK, const bf16* V, const bf16* PBUF, const float* DBUF, bf16* Y, const float* onw) {
;     ...
;         FINISH(31);
;     ...
;         return;
	v_lshlrev_b32_e32 v32, 16, v14
	v_and_b32_e32 v33, 0xffff0000, v14
	s_waitcnt lgkmcnt(1)
	v_mov_b32_e32 v18, v22
	s_waitcnt lgkmcnt(0)
	v_mov_b32_e32 v19, v26
	v_mov_b32_e32 v26, v23
	v_pk_add_f32 v[22:23], v[18:19], v[26:27]
	v_add_u32_e32 v18, v50, v105
	ds_read_b128 v[18:21], v18
	v_mov_b32_e32 v26, v24
	v_mov_b32_e32 v27, v28
	v_mov_b32_e32 v28, v25
	v_pk_add_f32 v[24:25], v[26:27], v[28:29]
	v_lshlrev_b32_e32 v36, 16, v15
	v_pk_add_f32 v[26:27], v[22:23], v[24:25]
	ds_read_b128 v[22:25], v45
	s_waitcnt lgkmcnt(1)
	v_lshlrev_b32_e32 v28, 16, v18
	v_and_b32_e32 v29, 0xffff0000, v18
	v_lshlrev_b32_e32 v34, 16, v19
	v_and_b32_e32 v35, 0xffff0000, v19
	v_lshlrev_b32_e32 v38, 16, v20
	v_and_b32_e32 v39, 0xffff0000, v20
	v_lshlrev_b32_e32 v42, 16, v21
	v_and_b32_e32 v43, 0xffff0000, v21
	ds_read_b128 v[18:21], v45 offset:16
	s_waitcnt lgkmcnt(1)
	v_mov_b32_e32 v46, v22
	v_mov_b32_e32 v22, v24
	v_and_b32_e32 v37, 0xffff0000, v15
	v_lshlrev_b32_e32 v40, 16, v16
	s_waitcnt lgkmcnt(0)
	v_mov_b32_e32 v47, v18
	v_mov_b32_e32 v18, v23
	v_mov_b32_e32 v23, v20
	v_mov_b32_e32 v20, v25
	v_pk_add_f32 v[18:19], v[46:47], v[18:19]
	v_pk_add_f32 v[20:21], v[22:23], v[20:21]
	v_and_b32_e32 v41, 0xffff0000, v16
	v_pk_add_f32 v[18:19], v[18:19], v[20:21]
	v_mov_b32_e32 v21, v26
	v_mov_b32_e32 v20, v18
	v_mov_b32_e32 v26, v19
	v_pk_add_f32 v[18:19], v[20:21], v[26:27]
	v_add_u32_e32 v14, v50, v97
	v_pk_fma_f32 v[22:23], v[18:19], s[0:1], v[30:31] op_sel_hi:[1,0,0]
	v_lshlrev_b32_e32 v44, 16, v17
	v_mul_f32_e32 v18, 0x4b800000, v23
	v_cmp_gt_f32_e32 vcc, s33, v23
	v_and_b32_e32 v45, 0xffff0000, v17
	ds_read_b128 v[14:17], v14
	v_cndmask_b32_e32 v18, v23, v18, vcc
	v_rsq_f32_e32 v20, v18
	v_lshl_add_u64 v[18:19], s[2:3], 0, v[88:89]
	v_lshlrev_b64 v[18:19], 11, v[18:19]
	v_lshl_add_u64 v[24:25], v[94:95], 0, v[18:19]
	v_mul_f32_e32 v18, 0x45800000, v20
	v_cndmask_b32_e32 v26, v20, v18, vcc
	v_pk_mul_f32 v[18:19], v[26:27], v[28:29] op_sel_hi:[0,1]
	v_pk_mul_f32 v[20:21], v[26:27], v[34:35] op_sel_hi:[0,1]
	v_pk_mul_f32 v[18:19], v[6:7], v[18:19]
	v_pk_mul_f32 v[20:21], v[8:9], v[20:21]
	v_pk_mul_f32 v[18:19], v[18:19], v[32:33]
	v_pk_mul_f32 v[20:21], v[20:21], v[36:37]
	v_cvt_pk_bf16_f32 v18, v18, v19
	v_cvt_pk_bf16_f32 v19, v20, v21
	v_pk_mul_f32 v[20:21], v[26:27], v[38:39] op_sel_hi:[0,1]
	v_pk_mul_f32 v[20:21], v[2:3], v[20:21]
	v_cmp_gt_f32_e32 vcc, s33, v22
	v_pk_mul_f32 v[20:21], v[20:21], v[40:41]
	v_pk_mul_f32 v[26:27], v[26:27], v[42:43] op_sel_hi:[0,1]
	v_cvt_pk_bf16_f32 v20, v20, v21
	v_mul_f32_e32 v21, 0x4b800000, v22
	v_cndmask_b32_e32 v21, v22, v21, vcc
	v_rsq_f32_e32 v28, v21
	v_pk_mul_f32 v[26:27], v[4:5], v[26:27]
	s_mov_b64 s[0:1], 0
	v_pk_mul_f32 v[22:23], v[26:27], v[44:45]
	s_nop 0
	v_cvt_pk_bf16_f32 v21, v22, v23
	global_store_dwordx4 v[24:25], v[18:21], off
	s_nop 1
	v_mul_f32_e32 v18, 0x45800000, v28
	v_cndmask_b32_e32 v18, v28, v18, vcc
	s_waitcnt lgkmcnt(0)
	v_lshlrev_b32_e32 v20, 16, v14
	v_and_b32_e32 v21, 0xffff0000, v14
	v_lshlrev_b32_e32 v14, 16, v15
	v_and_b32_e32 v15, 0xffff0000, v15
	v_pk_mul_f32 v[20:21], v[18:19], v[20:21] op_sel_hi:[0,1]
	v_pk_mul_f32 v[14:15], v[18:19], v[14:15] op_sel_hi:[0,1]
	v_pk_mul_f32 v[6:7], v[6:7], v[20:21]
	s_waitcnt vmcnt(3)
	v_lshlrev_b32_e32 v20, 16, v10
	v_and_b32_e32 v21, 0xffff0000, v10
	v_pk_mul_f32 v[8:9], v[8:9], v[14:15]
	v_lshlrev_b32_e32 v10, 16, v11
	v_and_b32_e32 v11, 0xffff0000, v11
	v_pk_mul_f32 v[6:7], v[6:7], v[20:21]
	v_pk_mul_f32 v[8:9], v[8:9], v[10:11]
	v_cvt_pk_bf16_f32 v6, v6, v7
	v_cvt_pk_bf16_f32 v7, v8, v9
	v_lshlrev_b32_e32 v8, 16, v16
	v_and_b32_e32 v9, 0xffff0000, v16
	v_pk_mul_f32 v[8:9], v[18:19], v[8:9] op_sel_hi:[0,1]
	v_pk_mul_f32 v[2:3], v[2:3], v[8:9]
	v_lshlrev_b32_e32 v8, 16, v12
	v_and_b32_e32 v9, 0xffff0000, v12
	v_pk_mul_f32 v[2:3], v[2:3], v[8:9]
	s_nop 0
	v_cvt_pk_bf16_f32 v8, v2, v3
	v_lshlrev_b32_e32 v2, 16, v17
	v_and_b32_e32 v3, 0xffff0000, v17
	v_pk_mul_f32 v[2:3], v[18:19], v[2:3] op_sel_hi:[0,1]
	v_pk_mul_f32 v[2:3], v[4:5], v[2:3]
	v_lshlrev_b32_e32 v4, 16, v13
	v_and_b32_e32 v5, 0xffff0000, v13
	v_pk_mul_f32 v[2:3], v[2:3], v[4:5]
	s_nop 0
	v_cvt_pk_bf16_f32 v9, v2, v3
	v_lshl_add_u64 v[2:3], s[2:3], 0, v[86:87]
	v_lshlrev_b64 v[2:3], 11, v[2:3]
	v_lshl_add_u64 v[2:3], v[94:95], 0, v[2:3]
	global_store_dwordx4 v[2:3], v[6:9], off
	s_setprio 0
